# GEMM K-loops: per-segment s_setprio flips removed, one static s_setprio 1 for waves 0-3 (older half) around each K-loop
# speedup vs baseline: 1.0076x; 1.0010x over previous
; template <class Epi, class Sched, bool ALIGN_EPI = false, bool SP2 = false>
; __device__ __forceinline__ void gemm_phase(PG8_LAS unsigned char* lds, const Gemm g, const Sched& S, const Epi& E, int wid_in) {
;     ...
;         const bool has_next = S.next(ui + 1, nxt);
;         const char* nA = has_next ? (const char*)g.A + (size_t)nxt.pm * tstep + (size_t)nxt.kt0 * kstep : cA; const char* nB = has_next ? (const char*)g.Bt + (size_t)nxt.pn * tstep + (size_t)nxt.kt0 * kstep : cB;
;         const int nt = cur.nkt;
;     ...
; #pragma unroll
;         for (int a = 0; a < 2; ++a)
; #pragma unroll
;             for (int b = 0; b < 2; ++b)
; #pragma unroll
;                 for (int m = 0; m < 4; ++m)
; #pragma unroll
;                     for (int n = 0; n < 2; ++n) acc[a][b][m][n] = (f32x4){0.f, 0.f, 0.f, 0.f};
.LBB0_277:
	s_ashr_i32 s19, s18, 31
	s_lshl_b64 s[22:23], s[18:19], 20
	s_add_u32 s22, s0, s22
	s_addc_u32 s23, s1, s23
	s_and_b64 s[24:25], s[20:21], exec
	s_cselect_b32 s11, s23, s27
	s_cselect_b32 s19, s22, s26
	s_ashr_i32 s17, s16, 31
	s_lshl_b64 s[24:25], s[16:17], 20
	s_add_u32 s24, s34, s24
	s_addc_u32 s25, s35, s25
	s_and_b64 s[30:31], s[20:21], exec
	s_cselect_b32 s17, s25, s29
	s_cselect_b32 s62, s24, s28
	s_add_u32 s64, s28, 0x100
	s_addc_u32 s65, s29, 0
	s_add_u32 s26, s26, 0x80080
	v_mov_b32_e32 v2, 0
	s_addc_u32 s27, s27, 0
	s_mov_b32 s63, -2
	v_mov_b32_e32 v3, v2
	v_mov_b32_e32 v4, v2
	v_mov_b32_e32 v5, v2
	v_mov_b32_e32 v6, v2
	v_mov_b32_e32 v7, v2
	v_mov_b32_e32 v8, v2
	v_mov_b32_e32 v9, v2
	v_mov_b32_e32 v10, v2
	v_mov_b32_e32 v11, v2
	v_mov_b32_e32 v12, v2
	v_mov_b32_e32 v13, v2
	v_mov_b32_e32 v14, v2
	v_mov_b32_e32 v15, v2
	v_mov_b32_e32 v16, v2
	v_mov_b32_e32 v17, v2
	v_mov_b32_e32 v26, v2
	v_mov_b32_e32 v27, v2
	v_mov_b32_e32 v28, v2
	v_mov_b32_e32 v29, v2
	v_mov_b32_e32 v30, v2
	v_mov_b32_e32 v31, v2
	v_mov_b32_e32 v32, v2
	v_mov_b32_e32 v33, v2
	v_mov_b32_e32 v42, v2
	v_mov_b32_e32 v43, v2
	v_mov_b32_e32 v44, v2
	v_mov_b32_e32 v45, v2
	v_mov_b32_e32 v46, v2
	v_mov_b32_e32 v47, v2
	v_mov_b32_e32 v48, v2
	v_mov_b32_e32 v49, v2
	v_mov_b32_e32 v18, v2
	v_mov_b32_e32 v19, v2
	v_mov_b32_e32 v20, v2
	v_mov_b32_e32 v21, v2
	v_mov_b32_e32 v22, v2
	v_mov_b32_e32 v23, v2
	v_mov_b32_e32 v24, v2
	v_mov_b32_e32 v25, v2
	v_mov_b32_e32 v34, v2
	v_mov_b32_e32 v35, v2
	v_mov_b32_e32 v36, v2
	v_mov_b32_e32 v37, v2
	v_mov_b32_e32 v38, v2
	v_mov_b32_e32 v39, v2
	v_mov_b32_e32 v40, v2
	v_mov_b32_e32 v41, v2
	v_mov_b32_e32 v50, v2
	v_mov_b32_e32 v51, v2
	v_mov_b32_e32 v52, v2
	v_mov_b32_e32 v53, v2
	v_mov_b32_e32 v54, v2
	v_mov_b32_e32 v55, v2
	v_mov_b32_e32 v56, v2
	v_mov_b32_e32 v57, v2
	v_mov_b32_e32 v58, v2
	v_mov_b32_e32 v59, v2
	v_mov_b32_e32 v60, v2
	v_mov_b32_e32 v61, v2
	v_mov_b32_e32 v62, v2
	v_mov_b32_e32 v63, v2
	v_mov_b32_e32 v64, v2
	v_mov_b32_e32 v65, v2
	v_mov_b32_e32 v66, v2
	v_mov_b32_e32 v67, v2
	v_mov_b32_e32 v68, v2
	v_mov_b32_e32 v69, v2
	v_mov_b32_e32 v70, v2
	v_mov_b32_e32 v71, v2
	v_mov_b32_e32 v72, v2
	v_mov_b32_e32 v73, v2
	v_mov_b32_e32 v74, v2
	v_mov_b32_e32 v75, v2
	v_mov_b32_e32 v76, v2
	v_mov_b32_e32 v77, v2
	v_mov_b32_e32 v78, v2
	v_mov_b32_e32 v79, v2
	v_mov_b32_e32 v80, v2
	v_mov_b32_e32 v81, v2
	v_mov_b32_e32 v90, v2
	v_mov_b32_e32 v91, v2
	v_mov_b32_e32 v92, v2
	v_mov_b32_e32 v93, v2
	v_mov_b32_e32 v94, v2
	v_mov_b32_e32 v95, v2
	v_mov_b32_e32 v96, v2
	v_mov_b32_e32 v97, v2
	v_mov_b32_e32 v106, v2
	v_mov_b32_e32 v107, v2
	v_mov_b32_e32 v108, v2
	v_mov_b32_e32 v109, v2
	v_mov_b32_e32 v110, v2
	v_mov_b32_e32 v111, v2
	v_mov_b32_e32 v112, v2
	v_mov_b32_e32 v113, v2
	v_mov_b32_e32 v82, v2
	v_mov_b32_e32 v83, v2
	v_mov_b32_e32 v84, v2
	v_mov_b32_e32 v85, v2
	v_mov_b32_e32 v86, v2
	v_mov_b32_e32 v87, v2
	v_mov_b32_e32 v88, v2
	v_mov_b32_e32 v89, v2
	v_mov_b32_e32 v98, v2
	v_mov_b32_e32 v99, v2
	v_mov_b32_e32 v100, v2
	v_mov_b32_e32 v101, v2
	v_mov_b32_e32 v102, v2
	v_mov_b32_e32 v103, v2
	v_mov_b32_e32 v104, v2
	v_mov_b32_e32 v105, v2
	v_mov_b32_e32 v114, v2
	v_mov_b32_e32 v115, v2
	v_mov_b32_e32 v116, v2
	v_mov_b32_e32 v117, v2
	v_mov_b32_e32 v118, v2
	v_mov_b32_e32 v119, v2
	v_mov_b32_e32 v120, v2
	v_mov_b32_e32 v121, v2
	v_mov_b32_e32 v122, v2
	v_mov_b32_e32 v123, v2
	v_mov_b32_e32 v124, v2
	v_mov_b32_e32 v125, v2
	v_mov_b32_e32 v126, v2
	v_mov_b32_e32 v127, v2
	v_mov_b32_e32 v128, v2
	v_mov_b32_e32 v129, v2
	s_cmp_lt_u32 s47, 4
	s_cbranch_scc0 .Lprio_skip_0
	s_setprio 1

; template <class Epi, class Sched, bool ALIGN_EPI = false, bool SP2 = false>
; __device__ __forceinline__ void gemm_phase(PG8_LAS unsigned char* lds, const Gemm g, const Sched& S, const Epi& E, int wid_in) {
;     ...
;         const bool has_next = S.next(ui + 1, nxt);
;         const char* nA = has_next ? (const char*)g.A + (size_t)nxt.pm * tstep + (size_t)nxt.kt0 * kstep : cA; const char* nB = has_next ? (const char*)g.Bt + (size_t)nxt.pn * tstep + (size_t)nxt.kt0 * kstep : cB;
;         const int nt = cur.nkt;
;     ...
; #pragma unroll
;         for (int a = 0; a < 2; ++a)
; #pragma unroll
;             for (int b = 0; b < 2; ++b)
; #pragma unroll
;                 for (int m = 0; m < 4; ++m)
; #pragma unroll
;                     for (int n = 0; n < 2; ++n) acc[a][b][m][n] = (f32x4){0.f, 0.f, 0.f, 0.f};
.LBB0_847:
	s_ashr_i32 s19, s18, 31
	s_lshl_b64 s[22:23], s[18:19], 19
	s_add_u32 s17, s38, s22
	s_addc_u32 s19, s39, s23
	s_ashr_i32 s15, s14, 31
	s_lshl_b64 s[24:25], s[14:15], 7
	s_add_u32 s22, s17, s24
	s_addc_u32 s23, s19, s25
	s_and_b64 s[36:37], s[20:21], exec
	s_cselect_b32 s15, s23, s35
	s_cselect_b32 s19, s22, s34
	s_ashr_i32 s17, s16, 31
	s_lshl_b64 s[36:37], s[16:17], 19
	s_add_u32 s17, s52, s36
	s_addc_u32 s27, s53, s37
	s_add_u32 s24, s17, s24
	s_addc_u32 s25, s27, s25
	s_and_b64 s[36:37], s[20:21], exec
	s_cselect_b32 s17, s25, s31
	s_cselect_b32 s27, s24, s30
	s_add_i32 vcc_lo, s1, -2
	s_add_u32 vcc_hi, s30, 0x100
	s_addc_u32 s63, s31, 0
	s_add_u32 s30, s34, 0x40080
	v_mov_b32_e32 v2, 0
	s_addc_u32 s31, s35, 0
	s_mov_b32 s34, 0
	v_mov_b32_e32 v3, v2
	v_mov_b32_e32 v4, v2
	v_mov_b32_e32 v5, v2
	v_mov_b32_e32 v6, v2
	v_mov_b32_e32 v7, v2
	v_mov_b32_e32 v8, v2
	v_mov_b32_e32 v9, v2
	v_mov_b32_e32 v10, v2
	v_mov_b32_e32 v11, v2
	v_mov_b32_e32 v12, v2
	v_mov_b32_e32 v13, v2
	v_mov_b32_e32 v14, v2
	v_mov_b32_e32 v15, v2
	v_mov_b32_e32 v16, v2
	v_mov_b32_e32 v17, v2
	v_mov_b32_e32 v26, v2
	v_mov_b32_e32 v27, v2
	v_mov_b32_e32 v28, v2
	v_mov_b32_e32 v29, v2
	v_mov_b32_e32 v30, v2
	v_mov_b32_e32 v31, v2
	v_mov_b32_e32 v32, v2
	v_mov_b32_e32 v33, v2
	v_mov_b32_e32 v42, v2
	v_mov_b32_e32 v43, v2
	v_mov_b32_e32 v44, v2
	v_mov_b32_e32 v45, v2
	v_mov_b32_e32 v46, v2
	v_mov_b32_e32 v47, v2
	v_mov_b32_e32 v48, v2
	v_mov_b32_e32 v49, v2
	v_mov_b32_e32 v18, v2
	v_mov_b32_e32 v19, v2
	v_mov_b32_e32 v20, v2
	v_mov_b32_e32 v21, v2
	v_mov_b32_e32 v22, v2
	v_mov_b32_e32 v23, v2
	v_mov_b32_e32 v24, v2
	v_mov_b32_e32 v25, v2
	v_mov_b32_e32 v34, v2
	v_mov_b32_e32 v35, v2
	v_mov_b32_e32 v36, v2
	v_mov_b32_e32 v37, v2
	v_mov_b32_e32 v38, v2
	v_mov_b32_e32 v39, v2
	v_mov_b32_e32 v40, v2
	v_mov_b32_e32 v41, v2
	v_mov_b32_e32 v50, v2
	v_mov_b32_e32 v51, v2
	v_mov_b32_e32 v52, v2
	v_mov_b32_e32 v53, v2
	v_mov_b32_e32 v54, v2
	v_mov_b32_e32 v55, v2
	v_mov_b32_e32 v56, v2
	v_mov_b32_e32 v57, v2
	v_mov_b32_e32 v58, v2
	v_mov_b32_e32 v59, v2
	v_mov_b32_e32 v60, v2
	v_mov_b32_e32 v61, v2
	v_mov_b32_e32 v62, v2
	v_mov_b32_e32 v63, v2
	v_mov_b32_e32 v64, v2
	v_mov_b32_e32 v65, v2
	v_mov_b32_e32 v66, v2
	v_mov_b32_e32 v67, v2
	v_mov_b32_e32 v68, v2
	v_mov_b32_e32 v69, v2
	v_mov_b32_e32 v70, v2
	v_mov_b32_e32 v71, v2
	v_mov_b32_e32 v72, v2
	v_mov_b32_e32 v73, v2
	v_mov_b32_e32 v74, v2
	v_mov_b32_e32 v75, v2
	v_mov_b32_e32 v76, v2
	v_mov_b32_e32 v77, v2
	v_mov_b32_e32 v78, v2
	v_mov_b32_e32 v79, v2
	v_mov_b32_e32 v80, v2
	v_mov_b32_e32 v81, v2
	v_mov_b32_e32 v90, v2
	v_mov_b32_e32 v91, v2
	v_mov_b32_e32 v92, v2
	v_mov_b32_e32 v93, v2
	v_mov_b32_e32 v94, v2
	v_mov_b32_e32 v95, v2
	v_mov_b32_e32 v96, v2
	v_mov_b32_e32 v97, v2
	v_mov_b32_e32 v106, v2
	v_mov_b32_e32 v107, v2
	v_mov_b32_e32 v108, v2
	v_mov_b32_e32 v109, v2
	v_mov_b32_e32 v110, v2
	v_mov_b32_e32 v111, v2
	v_mov_b32_e32 v112, v2
	v_mov_b32_e32 v113, v2
	v_mov_b32_e32 v82, v2
	v_mov_b32_e32 v83, v2
	v_mov_b32_e32 v84, v2
	v_mov_b32_e32 v85, v2
	v_mov_b32_e32 v86, v2
	v_mov_b32_e32 v87, v2
	v_mov_b32_e32 v88, v2
	v_mov_b32_e32 v89, v2
	v_mov_b32_e32 v98, v2
	v_mov_b32_e32 v99, v2
	v_mov_b32_e32 v100, v2
	v_mov_b32_e32 v101, v2
	v_mov_b32_e32 v102, v2
	v_mov_b32_e32 v103, v2
	v_mov_b32_e32 v104, v2
	v_mov_b32_e32 v105, v2
	v_mov_b32_e32 v114, v2
	v_mov_b32_e32 v115, v2
	v_mov_b32_e32 v116, v2
	v_mov_b32_e32 v117, v2
	v_mov_b32_e32 v118, v2
	v_mov_b32_e32 v119, v2
	v_mov_b32_e32 v120, v2
	v_mov_b32_e32 v121, v2
	v_mov_b32_e32 v122, v2
	v_mov_b32_e32 v123, v2
	v_mov_b32_e32 v124, v2
	v_mov_b32_e32 v125, v2
	v_mov_b32_e32 v126, v2
	v_mov_b32_e32 v127, v2
	v_mov_b32_e32 v128, v2
	v_mov_b32_e32 v129, v2
	s_cmp_lt_u32 s47, 4
	s_cbranch_scc0 .Lprio_skip_1
	s_setprio 1

; template <class Epi, class Sched, bool ALIGN_EPI = false, bool SP2 = false>
; __device__ __forceinline__ void gemm_phase(PG8_LAS unsigned char* lds, const Gemm g, const Sched& S, const Epi& E, int wid_in) {
;     ...
;         const bool has_next = S.next(ui + 1, nxt);
;         const char* nA = has_next ? (const char*)g.A + (size_t)nxt.pm * tstep + (size_t)nxt.kt0 * kstep : cA; const char* nB = has_next ? (const char*)g.Bt + (size_t)nxt.pn * tstep + (size_t)nxt.kt0 * kstep : cB;
;         const int nt = cur.nkt;
;         for (int t = 0; t < nt; t += 2) {
;             const bool last = (t == nt - 2);
;             const char* a1 = cA + (size_t)(t + 1) * kstep;
;             const char* a2 = last ? nA : cA + (size_t)(t + 2) * kstep; const char* b2 = last ? nB : cB + (size_t)(t + 2) * kstep;
;     ...
; #pragma unroll
;         for (int a = 0; a < 2; ++a)
; #pragma unroll
;             for (int b = 0; b < 2; ++b)
; #pragma unroll
;                 for (int m = 0; m < 4; ++m)
; #pragma unroll
;                     for (int n = 0; n < 2; ++n) acc[a][b][m][n] = (f32x4){0.f, 0.f, 0.f, 0.f};
.LBB0_1020:
	s_add_i32 s17, s90, -2
	s_add_u32 s19, s30, 0x100
	s_addc_u32 s21, s31, 0
	s_add_u32 s30, s34, 0x80080
	v_mov_b32_e32 v2, 0
	s_addc_u32 s31, s35, 0
	s_mov_b32 s27, 0
	v_mov_b32_e32 v3, v2
	v_mov_b32_e32 v4, v2
	v_mov_b32_e32 v5, v2
	v_mov_b32_e32 v6, v2
	v_mov_b32_e32 v7, v2
	v_mov_b32_e32 v8, v2
	v_mov_b32_e32 v9, v2
	v_mov_b32_e32 v10, v2
	v_mov_b32_e32 v11, v2
	v_mov_b32_e32 v12, v2
	v_mov_b32_e32 v13, v2
	v_mov_b32_e32 v14, v2
	v_mov_b32_e32 v15, v2
	v_mov_b32_e32 v16, v2
	v_mov_b32_e32 v17, v2
	v_mov_b32_e32 v26, v2
	v_mov_b32_e32 v27, v2
	v_mov_b32_e32 v28, v2
	v_mov_b32_e32 v29, v2
	v_mov_b32_e32 v30, v2
	v_mov_b32_e32 v31, v2
	v_mov_b32_e32 v32, v2
	v_mov_b32_e32 v33, v2
	v_mov_b32_e32 v42, v2
	v_mov_b32_e32 v43, v2
	v_mov_b32_e32 v44, v2
	v_mov_b32_e32 v45, v2
	v_mov_b32_e32 v46, v2
	v_mov_b32_e32 v47, v2
	v_mov_b32_e32 v48, v2
	v_mov_b32_e32 v49, v2
	v_mov_b32_e32 v18, v2
	v_mov_b32_e32 v19, v2
	v_mov_b32_e32 v20, v2
	v_mov_b32_e32 v21, v2
	v_mov_b32_e32 v22, v2
	v_mov_b32_e32 v23, v2
	v_mov_b32_e32 v24, v2
	v_mov_b32_e32 v25, v2
	v_mov_b32_e32 v34, v2
	v_mov_b32_e32 v35, v2
	v_mov_b32_e32 v36, v2
	v_mov_b32_e32 v37, v2
	v_mov_b32_e32 v38, v2
	v_mov_b32_e32 v39, v2
	v_mov_b32_e32 v40, v2
	v_mov_b32_e32 v41, v2
	v_mov_b32_e32 v50, v2
	v_mov_b32_e32 v51, v2
	v_mov_b32_e32 v52, v2
	v_mov_b32_e32 v53, v2
	v_mov_b32_e32 v54, v2
	v_mov_b32_e32 v55, v2
	v_mov_b32_e32 v56, v2
	v_mov_b32_e32 v57, v2
	v_mov_b32_e32 v58, v2
	v_mov_b32_e32 v59, v2
	v_mov_b32_e32 v60, v2
	v_mov_b32_e32 v61, v2
	v_mov_b32_e32 v62, v2
	v_mov_b32_e32 v63, v2
	v_mov_b32_e32 v64, v2
	v_mov_b32_e32 v65, v2
	v_mov_b32_e32 v66, v2
	v_mov_b32_e32 v67, v2
	v_mov_b32_e32 v68, v2
	v_mov_b32_e32 v69, v2
	v_mov_b32_e32 v70, v2
	v_mov_b32_e32 v71, v2
	v_mov_b32_e32 v72, v2
	v_mov_b32_e32 v73, v2
	v_mov_b32_e32 v74, v2
	v_mov_b32_e32 v75, v2
	v_mov_b32_e32 v76, v2
	v_mov_b32_e32 v77, v2
	v_mov_b32_e32 v78, v2
	v_mov_b32_e32 v79, v2
	v_mov_b32_e32 v80, v2
	v_mov_b32_e32 v81, v2
	v_mov_b32_e32 v90, v2
	v_mov_b32_e32 v91, v2
	v_mov_b32_e32 v92, v2
	v_mov_b32_e32 v93, v2
	v_mov_b32_e32 v94, v2
	v_mov_b32_e32 v95, v2
	v_mov_b32_e32 v96, v2
	v_mov_b32_e32 v97, v2
	v_mov_b32_e32 v106, v2
	v_mov_b32_e32 v107, v2
	v_mov_b32_e32 v108, v2
	v_mov_b32_e32 v109, v2
	v_mov_b32_e32 v110, v2
	v_mov_b32_e32 v111, v2
	v_mov_b32_e32 v112, v2
	v_mov_b32_e32 v113, v2
	v_mov_b32_e32 v82, v2
	v_mov_b32_e32 v83, v2
	v_mov_b32_e32 v84, v2
	v_mov_b32_e32 v85, v2
	v_mov_b32_e32 v86, v2
	v_mov_b32_e32 v87, v2
	v_mov_b32_e32 v88, v2
	v_mov_b32_e32 v89, v2
	v_mov_b32_e32 v98, v2
	v_mov_b32_e32 v99, v2
	v_mov_b32_e32 v100, v2
	v_mov_b32_e32 v101, v2
	v_mov_b32_e32 v102, v2
	v_mov_b32_e32 v103, v2
	v_mov_b32_e32 v104, v2
	v_mov_b32_e32 v105, v2
	v_mov_b32_e32 v114, v2
	v_mov_b32_e32 v115, v2
	v_mov_b32_e32 v116, v2
	v_mov_b32_e32 v117, v2
	v_mov_b32_e32 v118, v2
	v_mov_b32_e32 v119, v2
	v_mov_b32_e32 v120, v2
	v_mov_b32_e32 v121, v2
	v_mov_b32_e32 v122, v2
	v_mov_b32_e32 v123, v2
	v_mov_b32_e32 v124, v2
	v_mov_b32_e32 v125, v2
	v_mov_b32_e32 v126, v2
	v_mov_b32_e32 v127, v2
	v_mov_b32_e32 v128, v2
	v_mov_b32_e32 v129, v2
	s_cmp_lt_u32 s47, 4
	s_cbranch_scc0 .Lprio_skip_3
	s_setprio 1

; template <class Epi, class Sched, bool ALIGN_EPI = false, bool SP2 = false>
; __device__ __forceinline__ void gemm_phase(PG8_LAS unsigned char* lds, const Gemm g, const Sched& S, const Epi& E, int wid_in) {
;     ...
;         const bool has_next = S.next(ui + 1, nxt);
;         const char* nA = has_next ? (const char*)g.A + (size_t)nxt.pm * tstep + (size_t)nxt.kt0 * kstep : cA; const char* nB = has_next ? (const char*)g.Bt + (size_t)nxt.pn * tstep + (size_t)nxt.kt0 * kstep : cB;
;         const int nt = cur.nkt;
;     ...
; #pragma unroll
;         for (int a = 0; a < 2; ++a)
; #pragma unroll
;             for (int b = 0; b < 2; ++b)
; #pragma unroll
;                 for (int m = 0; m < 4; ++m)
; #pragma unroll
;                     for (int n = 0; n < 2; ++n) acc[a][b][m][n] = (f32x4){0.f, 0.f, 0.f, 0.f};
.LBB0_1152:
	s_ashr_i32 s19, s18, 31
	s_lshl_b64 s[20:21], s[18:19], 20
	s_add_u32 s20, s0, s20
	s_addc_u32 s21, s1, s21
	s_and_b64 s[22:23], s[8:9], exec
	s_cselect_b32 s19, s21, s25
	s_cselect_b32 s64, s20, s24
	s_ashr_i32 s17, s16, 31
	s_lshl_b64 s[22:23], s[16:17], 20
	s_add_u32 s22, s30, s22
	s_addc_u32 s23, s31, s23
	s_and_b64 s[28:29], s[8:9], exec
	s_cselect_b32 s17, s23, s27
	s_cselect_b32 s65, s22, s26
	s_add_u32 s72, s26, 0x100
	s_addc_u32 s63, s27, 0
	s_add_u32 s24, s24, 0x80080
	v_mov_b32_e32 v2, 0
	s_addc_u32 s25, s25, 0
	s_mov_b32 s73, -2
	v_mov_b32_e32 v3, v2
	v_mov_b32_e32 v4, v2
	v_mov_b32_e32 v5, v2
	v_mov_b32_e32 v6, v2
	v_mov_b32_e32 v7, v2
	v_mov_b32_e32 v8, v2
	v_mov_b32_e32 v9, v2
	v_mov_b32_e32 v18, v2
	v_mov_b32_e32 v19, v2
	v_mov_b32_e32 v20, v2
	v_mov_b32_e32 v21, v2
	v_mov_b32_e32 v22, v2
	v_mov_b32_e32 v23, v2
	v_mov_b32_e32 v24, v2
	v_mov_b32_e32 v25, v2
	v_mov_b32_e32 v34, v2
	v_mov_b32_e32 v35, v2
	v_mov_b32_e32 v36, v2
	v_mov_b32_e32 v37, v2
	v_mov_b32_e32 v38, v2
	v_mov_b32_e32 v39, v2
	v_mov_b32_e32 v40, v2
	v_mov_b32_e32 v41, v2
	v_mov_b32_e32 v50, v2
	v_mov_b32_e32 v51, v2
	v_mov_b32_e32 v52, v2
	v_mov_b32_e32 v53, v2
	v_mov_b32_e32 v54, v2
	v_mov_b32_e32 v55, v2
	v_mov_b32_e32 v56, v2
	v_mov_b32_e32 v57, v2
	v_mov_b32_e32 v10, v2
	v_mov_b32_e32 v11, v2
	v_mov_b32_e32 v12, v2
	v_mov_b32_e32 v13, v2
	v_mov_b32_e32 v14, v2
	v_mov_b32_e32 v15, v2
	v_mov_b32_e32 v16, v2
	v_mov_b32_e32 v17, v2
	v_mov_b32_e32 v26, v2
	v_mov_b32_e32 v27, v2
	v_mov_b32_e32 v28, v2
	v_mov_b32_e32 v29, v2
	v_mov_b32_e32 v30, v2
	v_mov_b32_e32 v31, v2
	v_mov_b32_e32 v32, v2
	v_mov_b32_e32 v33, v2
	v_mov_b32_e32 v42, v2
	v_mov_b32_e32 v43, v2
	v_mov_b32_e32 v44, v2
	v_mov_b32_e32 v45, v2
	v_mov_b32_e32 v46, v2
	v_mov_b32_e32 v47, v2
	v_mov_b32_e32 v48, v2
	v_mov_b32_e32 v49, v2
	v_mov_b32_e32 v58, v2
	v_mov_b32_e32 v59, v2
	v_mov_b32_e32 v60, v2
	v_mov_b32_e32 v61, v2
	v_mov_b32_e32 v62, v2
	v_mov_b32_e32 v63, v2
	v_mov_b32_e32 v64, v2
	v_mov_b32_e32 v65, v2
	v_mov_b32_e32 v66, v2
	v_mov_b32_e32 v67, v2
	v_mov_b32_e32 v68, v2
	v_mov_b32_e32 v69, v2
	v_mov_b32_e32 v70, v2
	v_mov_b32_e32 v71, v2
	v_mov_b32_e32 v72, v2
	v_mov_b32_e32 v73, v2
	v_mov_b32_e32 v82, v2
	v_mov_b32_e32 v83, v2
	v_mov_b32_e32 v84, v2
	v_mov_b32_e32 v85, v2
	v_mov_b32_e32 v86, v2
	v_mov_b32_e32 v87, v2
	v_mov_b32_e32 v88, v2
	v_mov_b32_e32 v89, v2
	v_mov_b32_e32 v98, v2
	v_mov_b32_e32 v99, v2
	v_mov_b32_e32 v100, v2
	v_mov_b32_e32 v101, v2
	v_mov_b32_e32 v102, v2
	v_mov_b32_e32 v103, v2
	v_mov_b32_e32 v104, v2
	v_mov_b32_e32 v105, v2
	v_mov_b32_e32 v114, v2
	v_mov_b32_e32 v115, v2
	v_mov_b32_e32 v116, v2
	v_mov_b32_e32 v117, v2
	v_mov_b32_e32 v118, v2
	v_mov_b32_e32 v119, v2
	v_mov_b32_e32 v120, v2
	v_mov_b32_e32 v121, v2
	v_mov_b32_e32 v74, v2
	v_mov_b32_e32 v75, v2
	v_mov_b32_e32 v76, v2
	v_mov_b32_e32 v77, v2
	v_mov_b32_e32 v78, v2
	v_mov_b32_e32 v79, v2
	v_mov_b32_e32 v80, v2
	v_mov_b32_e32 v81, v2
	v_mov_b32_e32 v90, v2
	v_mov_b32_e32 v91, v2
	v_mov_b32_e32 v92, v2
	v_mov_b32_e32 v93, v2
	v_mov_b32_e32 v94, v2
	v_mov_b32_e32 v95, v2
	v_mov_b32_e32 v96, v2
	v_mov_b32_e32 v97, v2
	v_mov_b32_e32 v106, v2
	v_mov_b32_e32 v107, v2
	v_mov_b32_e32 v108, v2
	v_mov_b32_e32 v109, v2
	v_mov_b32_e32 v110, v2
	v_mov_b32_e32 v111, v2
	v_mov_b32_e32 v112, v2
	v_mov_b32_e32 v113, v2
	v_mov_b32_e32 v122, v2
	v_mov_b32_e32 v123, v2
	v_mov_b32_e32 v124, v2
	v_mov_b32_e32 v125, v2
	v_mov_b32_e32 v126, v2
	v_mov_b32_e32 v127, v2
	v_mov_b32_e32 v128, v2
	v_mov_b32_e32 v129, v2
	s_cmp_lt_u32 s47, 4
	s_cbranch_scc0 .Lprio_skip_4
	s_setprio 1

; template <class Epi, class Sched, bool ALIGN_EPI = false, bool SP2 = false>
; __device__ __forceinline__ void gemm_phase(PG8_LAS unsigned char* lds, const Gemm g, const Sched& S, const Epi& E, int wid_in) {
;     ...
;         const bool has_next = S.next(ui + 1, nxt);
;         const char* nA = has_next ? (const char*)g.A + (size_t)nxt.pm * tstep + (size_t)nxt.kt0 * kstep : cA; const char* nB = has_next ? (const char*)g.Bt + (size_t)nxt.pn * tstep + (size_t)nxt.kt0 * kstep : cB;
;         const int nt = cur.nkt;
;         for (int t = 0; t < nt; t += 2) {
;             const bool last = (t == nt - 2);
;             const char* a1 = cA + (size_t)(t + 1) * kstep;
;             const char* a2 = last ? nA : cA + (size_t)(t + 2) * kstep; const char* b2 = last ? nB : cB + (size_t)(t + 2) * kstep;
;     ...
; #pragma unroll
;         for (int a = 0; a < 2; ++a)
; #pragma unroll
;             for (int b = 0; b < 2; ++b)
; #pragma unroll
;                 for (int m = 0; m < 4; ++m)
; #pragma unroll
;                     for (int n = 0; n < 2; ++n) acc[a][b][m][n] = (f32x4){0.f, 0.f, 0.f, 0.f};
.LBB0_1232:
	s_add_i32 s17, s90, -2
	s_add_u32 s19, s30, 0x100
	s_addc_u32 s21, s31, 0
	s_add_u32 s30, s34, 0x200080
	v_mov_b32_e32 v2, 0
	s_addc_u32 s31, s35, 0
	s_mov_b32 s27, 0
	v_mov_b32_e32 v3, v2
	v_mov_b32_e32 v4, v2
	v_mov_b32_e32 v5, v2
	v_mov_b32_e32 v6, v2
	v_mov_b32_e32 v7, v2
	v_mov_b32_e32 v8, v2
	v_mov_b32_e32 v9, v2
	v_mov_b32_e32 v10, v2
	v_mov_b32_e32 v11, v2
	v_mov_b32_e32 v12, v2
	v_mov_b32_e32 v13, v2
	v_mov_b32_e32 v14, v2
	v_mov_b32_e32 v15, v2
	v_mov_b32_e32 v16, v2
	v_mov_b32_e32 v17, v2
	v_mov_b32_e32 v26, v2
	v_mov_b32_e32 v27, v2
	v_mov_b32_e32 v28, v2
	v_mov_b32_e32 v29, v2
	v_mov_b32_e32 v30, v2
	v_mov_b32_e32 v31, v2
	v_mov_b32_e32 v32, v2
	v_mov_b32_e32 v33, v2
	v_mov_b32_e32 v42, v2
	v_mov_b32_e32 v43, v2
	v_mov_b32_e32 v44, v2
	v_mov_b32_e32 v45, v2
	v_mov_b32_e32 v46, v2
	v_mov_b32_e32 v47, v2
	v_mov_b32_e32 v48, v2
	v_mov_b32_e32 v49, v2
	v_mov_b32_e32 v18, v2
	v_mov_b32_e32 v19, v2
	v_mov_b32_e32 v20, v2
	v_mov_b32_e32 v21, v2
	v_mov_b32_e32 v22, v2
	v_mov_b32_e32 v23, v2
	v_mov_b32_e32 v24, v2
	v_mov_b32_e32 v25, v2
	v_mov_b32_e32 v34, v2
	v_mov_b32_e32 v35, v2
	v_mov_b32_e32 v36, v2
	v_mov_b32_e32 v37, v2
	v_mov_b32_e32 v38, v2
	v_mov_b32_e32 v39, v2
	v_mov_b32_e32 v40, v2
	v_mov_b32_e32 v41, v2
	v_mov_b32_e32 v50, v2
	v_mov_b32_e32 v51, v2
	v_mov_b32_e32 v52, v2
	v_mov_b32_e32 v53, v2
	v_mov_b32_e32 v54, v2
	v_mov_b32_e32 v55, v2
	v_mov_b32_e32 v56, v2
	v_mov_b32_e32 v57, v2
	v_mov_b32_e32 v58, v2
	v_mov_b32_e32 v59, v2
	v_mov_b32_e32 v60, v2
	v_mov_b32_e32 v61, v2
	v_mov_b32_e32 v62, v2
	v_mov_b32_e32 v63, v2
	v_mov_b32_e32 v64, v2
	v_mov_b32_e32 v65, v2
	v_mov_b32_e32 v66, v2
	v_mov_b32_e32 v67, v2
	v_mov_b32_e32 v68, v2
	v_mov_b32_e32 v69, v2
	v_mov_b32_e32 v70, v2
	v_mov_b32_e32 v71, v2
	v_mov_b32_e32 v72, v2
	v_mov_b32_e32 v73, v2
	v_mov_b32_e32 v74, v2
	v_mov_b32_e32 v75, v2
	v_mov_b32_e32 v76, v2
	v_mov_b32_e32 v77, v2
	v_mov_b32_e32 v78, v2
	v_mov_b32_e32 v79, v2
	v_mov_b32_e32 v80, v2
	v_mov_b32_e32 v81, v2
	v_mov_b32_e32 v90, v2
	v_mov_b32_e32 v91, v2
	v_mov_b32_e32 v92, v2
	v_mov_b32_e32 v93, v2
	v_mov_b32_e32 v94, v2
	v_mov_b32_e32 v95, v2
	v_mov_b32_e32 v96, v2
	v_mov_b32_e32 v97, v2
	v_mov_b32_e32 v106, v2
	v_mov_b32_e32 v107, v2
	v_mov_b32_e32 v108, v2
	v_mov_b32_e32 v109, v2
	v_mov_b32_e32 v110, v2
	v_mov_b32_e32 v111, v2
	v_mov_b32_e32 v112, v2
	v_mov_b32_e32 v113, v2
	v_mov_b32_e32 v82, v2
	v_mov_b32_e32 v83, v2
	v_mov_b32_e32 v84, v2
	v_mov_b32_e32 v85, v2
	v_mov_b32_e32 v86, v2
	v_mov_b32_e32 v87, v2
	v_mov_b32_e32 v88, v2
	v_mov_b32_e32 v89, v2
	v_mov_b32_e32 v98, v2
	v_mov_b32_e32 v99, v2
	v_mov_b32_e32 v100, v2
	v_mov_b32_e32 v101, v2
	v_mov_b32_e32 v102, v2
	v_mov_b32_e32 v103, v2
	v_mov_b32_e32 v104, v2
	v_mov_b32_e32 v105, v2
	v_mov_b32_e32 v114, v2
	v_mov_b32_e32 v115, v2
	v_mov_b32_e32 v116, v2
	v_mov_b32_e32 v117, v2
	v_mov_b32_e32 v118, v2
	v_mov_b32_e32 v119, v2
	v_mov_b32_e32 v120, v2
	v_mov_b32_e32 v121, v2
	v_mov_b32_e32 v122, v2
	v_mov_b32_e32 v123, v2
	v_mov_b32_e32 v124, v2
	v_mov_b32_e32 v125, v2
	v_mov_b32_e32 v126, v2
	v_mov_b32_e32 v127, v2
	v_mov_b32_e32 v128, v2
	v_mov_b32_e32 v129, v2
	s_cmp_lt_u32 s47, 4
	s_cbranch_scc0 .Lprio_skip_5
	s_setprio 1
